# attention hot loop rescheduled (K reads before DMA, V reads hoisted to private register ring, decision chain behind first PV MFMAs, DMA m0 save/restore removed) + P0a + cg
# speedup vs baseline: 1.0123x; 1.0113x over previous
.LBB0_695:
	s_lshl_b32 s43, s34, 13
	s_mov_b32 s42, s38
	v_lshl_add_u32 v185, s42, 13, v184
	ds_read_b128 v[112:115], v185 offset:49152
	ds_read_b128 v[186:189], v185 offset:49664
	s_add_i32 s38, s43, s39
	s_mov_b32 m0, s38
	v_lshl_add_u64 v[202:203], s[68:69], 0, v[166:167]
	global_load_lds_dwordx4 v[172:173], off
	s_lshl_b32 s38, s34, 14
	s_add_i32 s45, s38, s24
	s_mov_b32 m0, s45
	v_lshl_add_u64 v[204:205], s[68:69], 0, v[170:171]
	global_load_lds_dwordx4 v[202:203], off
	s_add_i32 s38, s38, s25
	s_mov_b32 m0, s38
	s_mov_b32 s38, s44
	global_load_lds_dwordx4 v[204:205], off
	s_waitcnt lgkmcnt(1)
	v_mfma_f32_32x32x16_bf16 v[128:143], v[112:115], v[156:159], v[64:79]
	ds_read_b128 v[190:193], v185 offset:51200
	ds_read_b128 v[194:197], v185 offset:51712
	v_add_f32_e32 v116, 0, v96
	v_add_f32_e32 v117, 0, v97
	v_add_f32_e32 v116, v98, v116
	v_add_f32_e32 v117, v99, v117
	v_cvt_pk_bf16_f32 v96, v96, v97
	v_cvt_pk_bf16_f32 v97, v98, v99
	v_cvt_pk_bf16_f32 v98, v100, v101
	v_cvt_pk_bf16_f32 v99, v102, v103
	s_nop 0
	v_add_f32_e32 v100, v100, v116
	v_add_f32_e32 v101, v101, v117
	s_waitcnt lgkmcnt(2)
	v_mfma_f32_32x32x16_bf16 v[112:127], v[186:189], v[156:159], v[64:79]
	v_add_f32_e32 v100, v102, v100
	v_add_f32_e32 v101, v103, v101
	v_permlane32_swap_b32_e32 v96, v98
	v_permlane32_swap_b32_e32 v97, v99
	s_waitcnt lgkmcnt(1)
	v_mfma_f32_32x32x16_bf16 v[128:143], v[190:193], v[152:155], v[128:143]
	ds_read_b128 v[186:189], v185 offset:53248
	ds_read_b128 v[198:201], v185 offset:53760
	v_add_f32_e32 v100, v104, v100
	v_add_f32_e32 v101, v105, v101
	v_add_f32_e32 v202, v106, v100
	v_add_f32_e32 v203, v107, v101
	v_cvt_pk_bf16_f32 v100, v104, v105
	v_cvt_pk_bf16_f32 v101, v106, v107
	v_cvt_pk_bf16_f32 v102, v108, v109
	v_cvt_pk_bf16_f32 v103, v110, v111
	s_waitcnt lgkmcnt(2)
	v_mfma_f32_32x32x16_bf16 v[112:127], v[194:197], v[152:155], v[112:127]
	v_add_f32_e32 v104, v108, v202
	v_add_f32_e32 v105, v109, v203
	v_add_f32_e32 v190, v110, v104
	v_add_f32_e32 v191, v111, v105
	v_permlane32_swap_b32_e32 v100, v102
	v_permlane32_swap_b32_e32 v101, v103
	s_waitcnt lgkmcnt(1)
	v_mfma_f32_32x32x16_bf16 v[128:143], v[186:189], v[148:151], v[128:143]
	ds_read_b128 v[104:107], v185 offset:55296
	ds_read_b128 v[108:111], v185 offset:55808
	v_add_f32_e32 v185, v80, v190
	v_add_f32_e32 v190, v81, v191
	v_add_f32_e32 v185, v82, v185
	v_add_f32_e32 v190, v83, v190
	v_cvt_pk_bf16_f32 v80, v80, v81
	v_cvt_pk_bf16_f32 v81, v82, v83
	v_cvt_pk_bf16_f32 v82, v84, v85
	v_cvt_pk_bf16_f32 v83, v86, v87
	s_waitcnt lgkmcnt(2)
	v_mfma_f32_32x32x16_bf16 v[112:127], v[198:201], v[148:151], v[112:127]
	s_lshl_b32 s44, s38, 14
	v_add_u32_e32 v189, s44, v183
	ds_read_b64_tr_b16 v[194:195], v189 offset:0
	ds_read_b64_tr_b16 v[196:197], v189 offset:0x800
	v_add_f32_e32 v84, v84, v185
	v_add_f32_e32 v85, v85, v190
	v_add_f32_e32 v84, v86, v84
	v_add_f32_e32 v85, v87, v85
	v_permlane32_swap_b32_e32 v80, v82
	v_permlane32_swap_b32_e32 v81, v83
	s_waitcnt lgkmcnt(3)
	v_mfma_f32_32x32x16_bf16 v[128:143], v[104:107], v[144:147], v[128:143]
	ds_read_b64_tr_b16 v[190:191], v189 offset:0x1000
	ds_read_b64_tr_b16 v[192:193], v189 offset:0x1800
	v_add_f32_e32 v84, v88, v84
	v_add_f32_e32 v85, v89, v85
	v_add_f32_e32 v185, v90, v84
	v_add_f32_e32 v186, v91, v85
	v_cvt_pk_bf16_f32 v84, v88, v89
	v_cvt_pk_bf16_f32 v85, v90, v91
	v_cvt_pk_bf16_f32 v86, v92, v93
	v_cvt_pk_bf16_f32 v87, v94, v95
	s_waitcnt lgkmcnt(4)
	v_mfma_f32_32x32x16_bf16 v[112:127], v[108:111], v[144:147], v[112:127]
	v_add_f32_e32 v88, v92, v185
	v_add_f32_e32 v89, v93, v186
	v_add_f32_e32 v88, v94, v88
	v_add_f32_e32 v89, v95, v89
	v_permlane32_swap_b32_e32 v84, v86
	v_permlane32_swap_b32_e32 v85, v87
	ds_read_b64_tr_b16 v[198:199], v189 offset:0x2000
	ds_read_b64_tr_b16 v[200:201], v189 offset:0x2800
	s_waitcnt lgkmcnt(4)
	v_mfma_f32_32x32x16_bf16 v[48:63], v[96:99], v[194:197], v[48:63]
	v_max_f32_e32 v90, v129, v129
	v_max_f32_e32 v91, v128, v128
	v_max_f32_e32 v90, v91, v90
	v_max3_f32 v91, v131, v132, v133
	v_max3_f32 v90, v90, v130, v134
	v_max3_f32 v91, v91, v136, v137
	ds_read_b64_tr_b16 v[194:195], v189 offset:0x3000
	ds_read_b64_tr_b16 v[196:197], v189 offset:0x3800
	s_waitcnt lgkmcnt(4)
	v_mfma_f32_32x32x16_bf16 v[48:63], v[100:103], v[190:193], v[48:63]
	v_max3_f32 v90, v90, v135, v138
	v_max3_f32 v91, v91, v140, v141
	v_max3_f32 v90, v90, v139, v142
	v_max3_f32 v90, v90, v143, v91
	v_add_f32_e32 v186, v88, v89
	v_mov_b32_e32 v187, v186
	ds_read_b64_tr_b16 v[190:191], v189 offset:0x200
	ds_read_b64_tr_b16 v[192:193], v189 offset:0xa00
	s_waitcnt lgkmcnt(4)
	v_mfma_f32_32x32x16_bf16 v[48:63], v[80:83], v[198:201], v[48:63]
	v_max3_f32 v88, v112, v113, v114
	v_max3_f32 v89, v115, v116, v117
	v_max3_f32 v88, v88, v118, v119
	v_max3_f32 v89, v89, v120, v121
	v_permlane32_swap_b32_e32 v186, v187
	v_max3_f32 v88, v88, v122, v123
	ds_read_b64_tr_b16 v[198:199], v189 offset:0x1200
	ds_read_b64_tr_b16 v[200:201], v189 offset:0x1a00
	s_waitcnt lgkmcnt(4)
	v_mfma_f32_32x32x16_bf16 v[48:63], v[84:87], v[194:197], v[48:63]
	v_max3_f32 v89, v89, v124, v125
	v_max3_f32 v88, v88, v126, v127
	v_max3_f32 v88, v90, v88, v89
	v_mov_b32_e32 v89, v88
	ds_read_b64_tr_b16 v[194:195], v189 offset:0x2200
	ds_read_b64_tr_b16 v[196:197], v189 offset:0x2a00
	s_waitcnt lgkmcnt(4)
	v_mfma_f32_32x32x16_bf16 v[32:47], v[96:99], v[190:193], v[32:47]
	v_permlane32_swap_b32_e32 v88, v89
	v_max_f32_e32 v89, v89, v89
	v_max_f32_e32 v88, v88, v88
	v_max_f32_e32 v88, v88, v89
	v_cmp_lt_f32_e32 vcc, s47, v88
	v_mov_b32_e32 v188, 1.0
	s_cbranch_vccnz .LBB0_707
.Lattn_m0_res1:
	ds_read_b64_tr_b16 v[190:191], v189 offset:0x3200
	ds_read_b64_tr_b16 v[192:193], v189 offset:0x3a00
	s_waitcnt lgkmcnt(4)
	v_mfma_f32_32x32x16_bf16 v[32:47], v[100:103], v[198:201], v[32:47]
	v_exp_f32_e32 v128, v128
	v_exp_f32_e32 v129, v129
	v_exp_f32_e32 v130, v130
	ds_read_b64_tr_b16 v[198:199], v189 offset:0x400
	ds_read_b64_tr_b16 v[200:201], v189 offset:0xc00
	s_waitcnt lgkmcnt(4)
	v_mfma_f32_32x32x16_bf16 v[32:47], v[80:83], v[194:197], v[32:47]
	v_exp_f32_e32 v131, v131
	v_exp_f32_e32 v132, v132
	v_exp_f32_e32 v133, v133
	ds_read_b64_tr_b16 v[194:195], v189 offset:0x1400
	ds_read_b64_tr_b16 v[196:197], v189 offset:0x1c00
	s_waitcnt lgkmcnt(4)
	v_mfma_f32_32x32x16_bf16 v[32:47], v[84:87], v[190:193], v[32:47]
	v_exp_f32_e32 v134, v134
	v_exp_f32_e32 v135, v135
	v_exp_f32_e32 v136, v136
	ds_read_b64_tr_b16 v[190:191], v189 offset:0x2400
	ds_read_b64_tr_b16 v[192:193], v189 offset:0x2c00
	s_waitcnt lgkmcnt(4)
	v_mfma_f32_32x32x16_bf16 v[16:31], v[96:99], v[198:201], v[16:31]
	v_exp_f32_e32 v137, v137
	v_exp_f32_e32 v138, v138
	v_exp_f32_e32 v139, v139
	ds_read_b64_tr_b16 v[198:199], v189 offset:0x3400
	ds_read_b64_tr_b16 v[200:201], v189 offset:0x3c00
	s_waitcnt lgkmcnt(4)
	v_mfma_f32_32x32x16_bf16 v[16:31], v[100:103], v[194:197], v[16:31]
	v_exp_f32_e32 v140, v140
	v_exp_f32_e32 v141, v141
	v_exp_f32_e32 v142, v142
	ds_read_b64_tr_b16 v[194:195], v189 offset:0x600
	ds_read_b64_tr_b16 v[196:197], v189 offset:0xe00
	s_waitcnt lgkmcnt(4)
	v_mfma_f32_32x32x16_bf16 v[16:31], v[80:83], v[190:193], v[16:31]
	v_exp_f32_e32 v143, v143
	v_exp_f32_e32 v112, v112
	v_exp_f32_e32 v113, v113
	ds_read_b64_tr_b16 v[190:191], v189 offset:0x1600
	ds_read_b64_tr_b16 v[192:193], v189 offset:0x1e00
	s_waitcnt lgkmcnt(4)
	v_mfma_f32_32x32x16_bf16 v[16:31], v[84:87], v[198:201], v[16:31]
	v_exp_f32_e32 v114, v114
	v_exp_f32_e32 v115, v115
	v_exp_f32_e32 v116, v116
	ds_read_b64_tr_b16 v[198:199], v189 offset:0x2600
	ds_read_b64_tr_b16 v[200:201], v189 offset:0x2e00
	s_waitcnt lgkmcnt(4)
	v_mfma_f32_32x32x16_bf16 v[0:15], v[96:99], v[194:197], v[0:15]
	v_exp_f32_e32 v117, v117
	v_exp_f32_e32 v118, v118
	v_exp_f32_e32 v119, v119
	ds_read_b64_tr_b16 v[194:195], v189 offset:0x3600
	ds_read_b64_tr_b16 v[196:197], v189 offset:0x3e00
	s_waitcnt lgkmcnt(4)
	v_mfma_f32_32x32x16_bf16 v[0:15], v[100:103], v[190:193], v[0:15]
	v_exp_f32_e32 v120, v120
	v_exp_f32_e32 v121, v121
	v_exp_f32_e32 v122, v122
	s_waitcnt lgkmcnt(2)
	v_mfma_f32_32x32x16_bf16 v[0:15], v[80:83], v[198:201], v[0:15]
	v_exp_f32_e32 v123, v123
	v_exp_f32_e32 v124, v124
	v_exp_f32_e32 v125, v125
	s_waitcnt lgkmcnt(0)
	v_mfma_f32_32x32x16_bf16 v[0:15], v[84:87], v[194:197], v[0:15]
	v_exp_f32_e32 v126, v126
	v_exp_f32_e32 v127, v127
	v_cmp_gt_f32_e32 vcc, 1.0, v188
	s_cbranch_vccz .LBB0_700
	s_and_saveexec_b64 s[70:71], s[0:1]
	ds_write_b32 v177, v188 offset:128
	s_or_b64 exec, exec, s[70:71]
	s_waitcnt lgkmcnt(0)
	v_add_u32_e32 v92, s19, v168
	ds_read_b128 v[80:83], v92 offset:224
	ds_read_b128 v[84:87], v92 offset:192
	ds_read_b128 v[88:91], v92 offset:160
	ds_read_b128 v[92:95], v92 offset:128
	s_waitcnt lgkmcnt(3)
	v_pk_mul_f32 v[60:61], v[60:61], v[80:81]
	s_waitcnt lgkmcnt(2)
	v_pk_mul_f32 v[56:57], v[56:57], v[84:85]
	s_waitcnt lgkmcnt(1)
	v_pk_mul_f32 v[52:53], v[52:53], v[88:89]
	v_pk_mul_f32 v[62:63], v[62:63], v[82:83]
	v_pk_mul_f32 v[58:59], v[58:59], v[86:87]
	v_pk_mul_f32 v[54:55], v[54:55], v[90:91]
	s_waitcnt lgkmcnt(0)
	v_pk_mul_f32 v[50:51], v[50:51], v[94:95]
	v_pk_mul_f32 v[48:49], v[48:49], v[92:93]
	v_pk_mul_f32 v[44:45], v[44:45], v[80:81]
	v_pk_mul_f32 v[40:41], v[40:41], v[84:85]
	v_pk_mul_f32 v[36:37], v[36:37], v[88:89]
	v_pk_mul_f32 v[46:47], v[46:47], v[82:83]
	v_pk_mul_f32 v[42:43], v[42:43], v[86:87]
	v_pk_mul_f32 v[38:39], v[38:39], v[90:91]
	v_pk_mul_f32 v[34:35], v[34:35], v[94:95]
	v_pk_mul_f32 v[32:33], v[32:33], v[92:93]
	v_pk_mul_f32 v[28:29], v[28:29], v[80:81]
	v_pk_mul_f32 v[24:25], v[24:25], v[84:85]
	v_pk_mul_f32 v[20:21], v[20:21], v[88:89]
	v_pk_mul_f32 v[30:31], v[30:31], v[82:83]
	v_pk_mul_f32 v[26:27], v[26:27], v[86:87]
	v_pk_mul_f32 v[22:23], v[22:23], v[90:91]
	v_pk_mul_f32 v[18:19], v[18:19], v[94:95]
	v_pk_mul_f32 v[16:17], v[16:17], v[92:93]
	v_pk_mul_f32 v[12:13], v[12:13], v[80:81]
	v_pk_mul_f32 v[8:9], v[8:9], v[84:85]
	v_pk_mul_f32 v[4:5], v[4:5], v[88:89]
	v_pk_mul_f32 v[14:15], v[14:15], v[82:83]
	v_pk_mul_f32 v[10:11], v[10:11], v[86:87]
	v_pk_mul_f32 v[6:7], v[6:7], v[90:91]
	v_pk_mul_f32 v[2:3], v[2:3], v[94:95]
	v_pk_mul_f32 v[0:1], v[0:1], v[92:93]
.LBB0_700:
	s_add_u32 s48, s68, 0x20000
	s_addc_u32 s49, s69, 0
	s_lshl_b32 s45, s38, 13
	s_add_i32 s45, s45, s39
	s_waitcnt vmcnt(0) lgkmcnt(0)
	s_barrier
	v_add_u32_e32 v185, s43, v184
	ds_read_b128 v[80:83], v185 offset:49152
	ds_read_b128 v[190:193], v185 offset:49664
	s_mov_b32 m0, s45
	v_lshl_add_u64 v[202:203], v[172:173], 0, s[8:9]
	global_load_lds_dwordx4 v[202:203], off
	s_add_i32 s45, s44, s24
	s_mov_b32 m0, s45
	v_lshl_add_u64 v[204:205], s[48:49], 0, v[166:167]
	global_load_lds_dwordx4 v[204:205], off
	s_add_i32 s44, s44, s25
	s_mov_b32 m0, s44
	v_lshl_add_u64 v[202:203], s[48:49], 0, v[170:171]
	global_load_lds_dwordx4 v[202:203], off
	s_waitcnt lgkmcnt(1)
	v_mfma_f32_32x32x16_bf16 v[96:111], v[80:83], v[156:159], v[64:79]
	ds_read_b128 v[194:197], v185 offset:51200
	ds_read_b128 v[198:201], v185 offset:51712
	v_add_f32_e32 v84, 0, v128
	v_add_f32_e32 v85, 0, v129
	v_add_f32_e32 v84, v130, v84
	v_add_f32_e32 v85, v131, v85
	v_cvt_pk_bf16_f32 v128, v128, v129
	v_cvt_pk_bf16_f32 v129, v130, v131
	v_cvt_pk_bf16_f32 v130, v132, v133
	v_cvt_pk_bf16_f32 v131, v134, v135
	s_nop 0
	v_add_f32_e32 v80, v132, v84
	v_add_f32_e32 v81, v133, v85
	v_add_f32_e32 v132, v134, v80
	v_add_f32_e32 v133, v135, v81
	s_waitcnt lgkmcnt(2)
	v_mfma_f32_32x32x16_bf16 v[80:95], v[190:193], v[156:159], v[64:79]
	v_permlane32_swap_b32_e32 v128, v130
	v_permlane32_swap_b32_e32 v129, v131
	s_waitcnt lgkmcnt(1)
	v_mfma_f32_32x32x16_bf16 v[96:111], v[194:197], v[152:155], v[96:111]
	ds_read_b128 v[190:193], v185 offset:53248
	ds_read_b128 v[202:205], v185 offset:53760
	v_add_f32_e32 v132, v136, v132
	v_add_f32_e32 v133, v137, v133
	v_add_f32_e32 v189, v138, v132
	v_add_f32_e32 v206, v139, v133
	v_cvt_pk_bf16_f32 v132, v136, v137
	v_cvt_pk_bf16_f32 v133, v138, v139
	v_cvt_pk_bf16_f32 v134, v140, v141
	v_cvt_pk_bf16_f32 v135, v142, v143
	s_waitcnt lgkmcnt(2)
	v_mfma_f32_32x32x16_bf16 v[80:95], v[198:201], v[152:155], v[80:95]
	v_add_f32_e32 v136, v140, v189
	v_add_f32_e32 v137, v141, v206
	v_add_f32_e32 v189, v142, v136
	v_add_f32_e32 v194, v143, v137
	v_permlane32_swap_b32_e32 v132, v134
	v_permlane32_swap_b32_e32 v133, v135
	s_waitcnt lgkmcnt(1)
	v_mfma_f32_32x32x16_bf16 v[96:111], v[190:193], v[148:151], v[96:111]
	ds_read_b128 v[136:139], v185 offset:55296
	ds_read_b128 v[140:143], v185 offset:55808
	v_add_f32_e32 v185, v112, v189
	v_add_f32_e32 v189, v113, v194
	v_add_f32_e32 v185, v114, v185
	v_add_f32_e32 v189, v115, v189
	v_cvt_pk_bf16_f32 v112, v112, v113
	v_cvt_pk_bf16_f32 v113, v114, v115
	v_cvt_pk_bf16_f32 v114, v116, v117
	v_cvt_pk_bf16_f32 v115, v118, v119
	s_waitcnt lgkmcnt(2)
	v_mfma_f32_32x32x16_bf16 v[80:95], v[202:205], v[148:151], v[80:95]
	v_lshl_add_u32 v206, s42, 14, v183
	ds_read_b64_tr_b16 v[198:199], v206 offset:0
	ds_read_b64_tr_b16 v[200:201], v206 offset:0x800
	v_add_f32_e32 v116, v116, v185
	v_add_f32_e32 v117, v117, v189
	v_add_f32_e32 v116, v118, v116
	v_add_f32_e32 v117, v119, v117
	v_permlane32_swap_b32_e32 v112, v114
	v_permlane32_swap_b32_e32 v113, v115
	s_waitcnt lgkmcnt(3)
	v_mfma_f32_32x32x16_bf16 v[96:111], v[136:139], v[144:147], v[96:111]
	ds_read_b64_tr_b16 v[190:191], v206 offset:0x1000
	ds_read_b64_tr_b16 v[192:193], v206 offset:0x1800
	v_add_f32_e32 v116, v120, v116
	v_add_f32_e32 v117, v121, v117
	v_add_f32_e32 v185, v122, v116
	v_add_f32_e32 v189, v123, v117
	v_cvt_pk_bf16_f32 v116, v120, v121
	v_cvt_pk_bf16_f32 v117, v122, v123
	v_cvt_pk_bf16_f32 v118, v124, v125
	v_cvt_pk_bf16_f32 v119, v126, v127
	s_waitcnt lgkmcnt(4)
	v_mfma_f32_32x32x16_bf16 v[80:95], v[140:143], v[144:147], v[80:95]
	v_add_f32_e32 v120, v124, v185
	v_add_f32_e32 v121, v125, v189
	v_add_f32_e32 v120, v126, v120
	v_add_f32_e32 v121, v127, v121
	v_permlane32_swap_b32_e32 v116, v118
	v_permlane32_swap_b32_e32 v117, v119
	ds_read_b64_tr_b16 v[202:203], v206 offset:0x2000
	ds_read_b64_tr_b16 v[204:205], v206 offset:0x2800
	s_waitcnt lgkmcnt(4)
	v_mfma_f32_32x32x16_bf16 v[48:63], v[128:131], v[198:201], v[48:63]
	v_max_f32_e32 v122, v97, v97
	v_max_f32_e32 v123, v96, v96
	v_max_f32_e32 v122, v123, v122
	v_max3_f32 v123, v99, v100, v101
	v_max3_f32 v122, v122, v98, v102
	v_max3_f32 v123, v123, v104, v105
	ds_read_b64_tr_b16 v[198:199], v206 offset:0x3000
	ds_read_b64_tr_b16 v[200:201], v206 offset:0x3800
	s_waitcnt lgkmcnt(4)
	v_mfma_f32_32x32x16_bf16 v[48:63], v[132:135], v[190:193], v[48:63]
	v_max3_f32 v122, v122, v103, v106
	v_max3_f32 v123, v123, v108, v109
	v_max3_f32 v122, v122, v107, v110
	v_max3_f32 v122, v122, v111, v123
	v_add_f32_e32 v120, v120, v121
	v_mov_b32_e32 v121, v120
	ds_read_b64_tr_b16 v[190:191], v206 offset:0x200
	ds_read_b64_tr_b16 v[192:193], v206 offset:0xa00
	s_waitcnt lgkmcnt(4)
	v_mfma_f32_32x32x16_bf16 v[48:63], v[112:115], v[202:205], v[48:63]
	v_max3_f32 v123, v80, v81, v82
	v_max3_f32 v124, v83, v84, v85
	v_max3_f32 v123, v123, v86, v87
	v_max3_f32 v124, v124, v88, v89
	v_permlane32_swap_b32_e32 v120, v121
	v_max3_f32 v123, v123, v90, v91
	ds_read_b64_tr_b16 v[202:203], v206 offset:0x1200
	ds_read_b64_tr_b16 v[204:205], v206 offset:0x1a00
	s_waitcnt lgkmcnt(4)
	v_mfma_f32_32x32x16_bf16 v[48:63], v[116:119], v[198:201], v[48:63]
	v_max3_f32 v124, v124, v92, v93
	v_max3_f32 v123, v123, v94, v95
	v_max3_f32 v122, v122, v123, v124
	v_mov_b32_e32 v123, v122
	ds_read_b64_tr_b16 v[198:199], v206 offset:0x2200
	ds_read_b64_tr_b16 v[200:201], v206 offset:0x2a00
	s_waitcnt lgkmcnt(4)
	v_mfma_f32_32x32x16_bf16 v[32:47], v[128:131], v[190:193], v[32:47]
	v_permlane32_swap_b32_e32 v122, v123
	v_max_f32_e32 v123, v123, v123
	v_max_f32_e32 v122, v122, v122
	v_max_f32_e32 v122, v122, v123
	v_cmp_lt_f32_e32 vcc, s47, v122
	v_mov_b32_e32 v185, 1.0
	s_cbranch_vccnz .LBB0_708
.Lattn_m0_res2:
	ds_read_b64_tr_b16 v[190:191], v206 offset:0x3200
	ds_read_b64_tr_b16 v[192:193], v206 offset:0x3a00
	s_waitcnt lgkmcnt(4)
	v_mfma_f32_32x32x16_bf16 v[32:47], v[132:135], v[202:205], v[32:47]
	v_exp_f32_e32 v96, v96
	v_exp_f32_e32 v97, v97
	v_exp_f32_e32 v98, v98
	ds_read_b64_tr_b16 v[202:203], v206 offset:0x400
	ds_read_b64_tr_b16 v[204:205], v206 offset:0xc00
	s_waitcnt lgkmcnt(4)
	v_mfma_f32_32x32x16_bf16 v[32:47], v[112:115], v[198:201], v[32:47]
	v_exp_f32_e32 v99, v99
	v_exp_f32_e32 v100, v100
	v_exp_f32_e32 v101, v101
	ds_read_b64_tr_b16 v[198:199], v206 offset:0x1400
	ds_read_b64_tr_b16 v[200:201], v206 offset:0x1c00
	s_waitcnt lgkmcnt(4)
	v_mfma_f32_32x32x16_bf16 v[32:47], v[116:119], v[190:193], v[32:47]
	v_exp_f32_e32 v102, v102
	v_exp_f32_e32 v103, v103
	v_exp_f32_e32 v104, v104
	ds_read_b64_tr_b16 v[190:191], v206 offset:0x2400
	ds_read_b64_tr_b16 v[192:193], v206 offset:0x2c00
	s_waitcnt lgkmcnt(4)
	v_mfma_f32_32x32x16_bf16 v[16:31], v[128:131], v[202:205], v[16:31]
	v_exp_f32_e32 v105, v105
	v_exp_f32_e32 v106, v106
	v_exp_f32_e32 v107, v107
	ds_read_b64_tr_b16 v[202:203], v206 offset:0x3400
	ds_read_b64_tr_b16 v[204:205], v206 offset:0x3c00
	s_waitcnt lgkmcnt(4)
	v_mfma_f32_32x32x16_bf16 v[16:31], v[132:135], v[198:201], v[16:31]
	v_exp_f32_e32 v108, v108
	v_exp_f32_e32 v109, v109
	v_exp_f32_e32 v110, v110
	ds_read_b64_tr_b16 v[198:199], v206 offset:0x600
	ds_read_b64_tr_b16 v[200:201], v206 offset:0xe00
	s_waitcnt lgkmcnt(4)
	v_mfma_f32_32x32x16_bf16 v[16:31], v[112:115], v[190:193], v[16:31]
	v_exp_f32_e32 v111, v111
	v_exp_f32_e32 v80, v80
	v_exp_f32_e32 v81, v81
	ds_read_b64_tr_b16 v[190:191], v206 offset:0x1600
	ds_read_b64_tr_b16 v[192:193], v206 offset:0x1e00
	s_waitcnt lgkmcnt(4)
	v_mfma_f32_32x32x16_bf16 v[16:31], v[116:119], v[202:205], v[16:31]
	v_exp_f32_e32 v82, v82
	v_exp_f32_e32 v83, v83
	v_exp_f32_e32 v84, v84
	ds_read_b64_tr_b16 v[202:203], v206 offset:0x2600
	ds_read_b64_tr_b16 v[204:205], v206 offset:0x2e00
	s_waitcnt lgkmcnt(4)
	v_mfma_f32_32x32x16_bf16 v[0:15], v[128:131], v[198:201], v[0:15]
	v_exp_f32_e32 v85, v85
	v_exp_f32_e32 v86, v86
	v_exp_f32_e32 v87, v87
	ds_read_b64_tr_b16 v[198:199], v206 offset:0x3600
	ds_read_b64_tr_b16 v[200:201], v206 offset:0x3e00
	s_waitcnt lgkmcnt(4)
	v_mfma_f32_32x32x16_bf16 v[0:15], v[132:135], v[190:193], v[0:15]
	v_exp_f32_e32 v88, v88
	v_exp_f32_e32 v89, v89
	v_exp_f32_e32 v90, v90
	s_waitcnt lgkmcnt(2)
	v_mfma_f32_32x32x16_bf16 v[0:15], v[112:115], v[202:205], v[0:15]
	v_exp_f32_e32 v91, v91
	v_exp_f32_e32 v92, v92
	v_exp_f32_e32 v93, v93
	s_waitcnt lgkmcnt(0)
	v_mfma_f32_32x32x16_bf16 v[0:15], v[116:119], v[198:201], v[0:15]
	v_exp_f32_e32 v94, v94
	v_exp_f32_e32 v95, v95
	v_cmp_gt_f32_e32 vcc, 1.0, v185
	s_cbranch_vccz .LBB0_705
	s_and_saveexec_b64 s[70:71], s[0:1]
	ds_write_b32 v177, v185 offset:128
	s_or_b64 exec, exec, s[70:71]
	s_waitcnt lgkmcnt(0)
	v_add_u32_e32 v126, s19, v168
	ds_read_b128 v[112:115], v126 offset:224
	ds_read_b128 v[116:119], v126 offset:192
	ds_read_b128 v[122:125], v126 offset:160
	ds_read_b128 v[126:129], v126 offset:128
	s_waitcnt lgkmcnt(3)
	v_pk_mul_f32 v[60:61], v[60:61], v[112:113]
	s_waitcnt lgkmcnt(2)
	v_pk_mul_f32 v[56:57], v[56:57], v[116:117]
	s_waitcnt lgkmcnt(1)
	v_pk_mul_f32 v[52:53], v[52:53], v[122:123]
	v_pk_mul_f32 v[62:63], v[62:63], v[114:115]
	v_pk_mul_f32 v[58:59], v[58:59], v[118:119]
	v_pk_mul_f32 v[54:55], v[54:55], v[124:125]
	s_waitcnt lgkmcnt(0)
	v_pk_mul_f32 v[50:51], v[50:51], v[128:129]
	v_pk_mul_f32 v[48:49], v[48:49], v[126:127]
	v_pk_mul_f32 v[44:45], v[44:45], v[112:113]
	v_pk_mul_f32 v[40:41], v[40:41], v[116:117]
	v_pk_mul_f32 v[36:37], v[36:37], v[122:123]
	v_pk_mul_f32 v[46:47], v[46:47], v[114:115]
	v_pk_mul_f32 v[42:43], v[42:43], v[118:119]
	v_pk_mul_f32 v[38:39], v[38:39], v[124:125]
	v_pk_mul_f32 v[34:35], v[34:35], v[128:129]
	v_pk_mul_f32 v[32:33], v[32:33], v[126:127]
	v_pk_mul_f32 v[28:29], v[28:29], v[112:113]
	v_pk_mul_f32 v[24:25], v[24:25], v[116:117]
	v_pk_mul_f32 v[20:21], v[20:21], v[122:123]
	v_pk_mul_f32 v[30:31], v[30:31], v[114:115]
	v_pk_mul_f32 v[26:27], v[26:27], v[118:119]
	v_pk_mul_f32 v[22:23], v[22:23], v[124:125]
	v_pk_mul_f32 v[18:19], v[18:19], v[128:129]
	v_pk_mul_f32 v[16:17], v[16:17], v[126:127]
	v_pk_mul_f32 v[12:13], v[12:13], v[112:113]
	v_pk_mul_f32 v[8:9], v[8:9], v[116:117]
	v_pk_mul_f32 v[4:5], v[4:5], v[122:123]
	v_pk_mul_f32 v[14:15], v[14:15], v[114:115]
	v_pk_mul_f32 v[10:11], v[10:11], v[118:119]
	v_pk_mul_f32 v[6:7], v[6:7], v[124:125]
	v_pk_mul_f32 v[2:3], v[2:3], v[128:129]
	v_pk_mul_f32 v[0:1], v[0:1], v[126:127]

.LBB0_720:
	s_lshl_b32 s43, s34, 13
	s_mov_b32 s42, s38
	v_lshl_add_u32 v187, s42, 13, v186
	ds_read_b128 v[112:115], v187 offset:49152
	ds_read_b128 v[188:191], v187 offset:49664
	s_add_i32 s38, s43, s39
	s_mov_b32 m0, s38
	v_lshl_add_u64 v[204:205], s[4:5], 0, v[166:167]
	global_load_lds_dwordx4 v[172:173], off
	s_lshl_b32 s38, s34, 14
	s_add_i32 s45, s38, s24
	s_mov_b32 m0, s45
	v_lshl_add_u64 v[206:207], s[4:5], 0, v[170:171]
	global_load_lds_dwordx4 v[204:205], off
	s_add_i32 s38, s38, s25
	s_mov_b32 m0, s38
	s_mov_b32 s38, s44
	global_load_lds_dwordx4 v[206:207], off
	s_waitcnt lgkmcnt(1)
	v_mfma_f32_32x32x16_bf16 v[128:143], v[112:115], v[156:159], v[64:79]
	ds_read_b128 v[192:195], v187 offset:51200
	ds_read_b128 v[196:199], v187 offset:51712
	v_add_f32_e32 v116, 0, v96
	v_add_f32_e32 v117, 0, v97
	v_add_f32_e32 v116, v98, v116
	v_add_f32_e32 v117, v99, v117
	v_cvt_pk_bf16_f32 v96, v96, v97
	v_cvt_pk_bf16_f32 v97, v98, v99
	v_cvt_pk_bf16_f32 v98, v100, v101
	v_cvt_pk_bf16_f32 v99, v102, v103
	s_nop 0
	v_add_f32_e32 v100, v100, v116
	v_add_f32_e32 v101, v101, v117
	s_waitcnt lgkmcnt(2)
	v_mfma_f32_32x32x16_bf16 v[112:127], v[188:191], v[156:159], v[64:79]
	v_add_f32_e32 v100, v102, v100
	v_add_f32_e32 v101, v103, v101
	v_permlane32_swap_b32_e32 v96, v98
	v_permlane32_swap_b32_e32 v97, v99
	s_waitcnt lgkmcnt(1)
	v_mfma_f32_32x32x16_bf16 v[128:143], v[192:195], v[152:155], v[128:143]
	ds_read_b128 v[188:191], v187 offset:53248
	ds_read_b128 v[200:203], v187 offset:53760
	v_add_f32_e32 v100, v104, v100
	v_add_f32_e32 v101, v105, v101
	v_add_f32_e32 v204, v106, v100
	v_add_f32_e32 v205, v107, v101
	v_cvt_pk_bf16_f32 v100, v104, v105
	v_cvt_pk_bf16_f32 v101, v106, v107
	v_cvt_pk_bf16_f32 v102, v108, v109
	v_cvt_pk_bf16_f32 v103, v110, v111
	s_waitcnt lgkmcnt(2)
	v_mfma_f32_32x32x16_bf16 v[112:127], v[196:199], v[152:155], v[112:127]
	v_add_f32_e32 v104, v108, v204
	v_add_f32_e32 v105, v109, v205
	v_add_f32_e32 v192, v110, v104
	v_add_f32_e32 v193, v111, v105
	v_permlane32_swap_b32_e32 v100, v102
	v_permlane32_swap_b32_e32 v101, v103
	s_waitcnt lgkmcnt(1)
	v_mfma_f32_32x32x16_bf16 v[128:143], v[188:191], v[148:151], v[128:143]
	ds_read_b128 v[104:107], v187 offset:55296
	ds_read_b128 v[108:111], v187 offset:55808
	v_add_f32_e32 v187, v80, v192
	v_add_f32_e32 v192, v81, v193
	v_add_f32_e32 v187, v82, v187
	v_add_f32_e32 v192, v83, v192
	v_cvt_pk_bf16_f32 v80, v80, v81
	v_cvt_pk_bf16_f32 v81, v82, v83
	v_cvt_pk_bf16_f32 v82, v84, v85
	v_cvt_pk_bf16_f32 v83, v86, v87
	s_waitcnt lgkmcnt(2)
	v_mfma_f32_32x32x16_bf16 v[112:127], v[200:203], v[148:151], v[112:127]
	s_lshl_b32 s44, s38, 14
	v_add_u32_e32 v191, s44, v185
	ds_read_b64_tr_b16 v[196:197], v191 offset:0
	ds_read_b64_tr_b16 v[198:199], v191 offset:0x800
	v_add_f32_e32 v84, v84, v187
	v_add_f32_e32 v85, v85, v192
	v_add_f32_e32 v84, v86, v84
	v_add_f32_e32 v85, v87, v85
	v_permlane32_swap_b32_e32 v80, v82
	v_permlane32_swap_b32_e32 v81, v83
	s_waitcnt lgkmcnt(3)
	v_mfma_f32_32x32x16_bf16 v[128:143], v[104:107], v[144:147], v[128:143]
	ds_read_b64_tr_b16 v[192:193], v191 offset:0x1000
	ds_read_b64_tr_b16 v[194:195], v191 offset:0x1800
	v_add_f32_e32 v84, v88, v84
	v_add_f32_e32 v85, v89, v85
	v_add_f32_e32 v187, v90, v84
	v_add_f32_e32 v188, v91, v85
	v_cvt_pk_bf16_f32 v84, v88, v89
	v_cvt_pk_bf16_f32 v85, v90, v91
	v_cvt_pk_bf16_f32 v86, v92, v93
	v_cvt_pk_bf16_f32 v87, v94, v95
	s_waitcnt lgkmcnt(4)
	v_mfma_f32_32x32x16_bf16 v[112:127], v[108:111], v[144:147], v[112:127]
	v_add_f32_e32 v88, v92, v187
	v_add_f32_e32 v89, v93, v188
	v_add_f32_e32 v88, v94, v88
	v_add_f32_e32 v89, v95, v89
	v_permlane32_swap_b32_e32 v84, v86
	v_permlane32_swap_b32_e32 v85, v87
	ds_read_b64_tr_b16 v[200:201], v191 offset:0x2000
	ds_read_b64_tr_b16 v[202:203], v191 offset:0x2800
	s_waitcnt lgkmcnt(4)
	v_mfma_f32_32x32x16_bf16 v[48:63], v[96:99], v[196:199], v[48:63]
	v_max_f32_e32 v90, v129, v129
	v_max_f32_e32 v91, v128, v128
	v_max_f32_e32 v90, v91, v90
	v_max3_f32 v91, v131, v132, v133
	v_max3_f32 v90, v90, v130, v134
	v_max3_f32 v91, v91, v136, v137
	ds_read_b64_tr_b16 v[196:197], v191 offset:0x3000
	ds_read_b64_tr_b16 v[198:199], v191 offset:0x3800
	s_waitcnt lgkmcnt(4)
	v_mfma_f32_32x32x16_bf16 v[48:63], v[100:103], v[192:195], v[48:63]
	v_max3_f32 v90, v90, v135, v138
	v_max3_f32 v91, v91, v140, v141
	v_max3_f32 v90, v90, v139, v142
	v_max3_f32 v90, v90, v143, v91
	v_add_f32_e32 v188, v88, v89
	v_mov_b32_e32 v189, v188
	ds_read_b64_tr_b16 v[192:193], v191 offset:0x200
	ds_read_b64_tr_b16 v[194:195], v191 offset:0xa00
	s_waitcnt lgkmcnt(4)
	v_mfma_f32_32x32x16_bf16 v[48:63], v[80:83], v[200:203], v[48:63]
	v_max3_f32 v88, v112, v113, v114
	v_max3_f32 v89, v115, v116, v117
	v_max3_f32 v88, v88, v118, v119
	v_max3_f32 v89, v89, v120, v121
	v_permlane32_swap_b32_e32 v188, v189
	v_max3_f32 v88, v88, v122, v123
	ds_read_b64_tr_b16 v[200:201], v191 offset:0x1200
	ds_read_b64_tr_b16 v[202:203], v191 offset:0x1a00
	s_waitcnt lgkmcnt(4)
	v_mfma_f32_32x32x16_bf16 v[48:63], v[84:87], v[196:199], v[48:63]
	v_max3_f32 v89, v89, v124, v125
	v_max3_f32 v88, v88, v126, v127
	v_max3_f32 v88, v90, v88, v89
	v_mov_b32_e32 v89, v88
	ds_read_b64_tr_b16 v[196:197], v191 offset:0x2200
	ds_read_b64_tr_b16 v[198:199], v191 offset:0x2a00
	s_waitcnt lgkmcnt(4)
	v_mfma_f32_32x32x16_bf16 v[32:47], v[96:99], v[192:195], v[32:47]
	v_permlane32_swap_b32_e32 v88, v89
	v_max_f32_e32 v89, v89, v89
	v_max_f32_e32 v88, v88, v88
	v_max_f32_e32 v88, v88, v89
	v_cmp_lt_f32_e32 vcc, s47, v88
	v_mov_b32_e32 v190, 1.0
	s_cbranch_vccnz .LBB0_732
.Lattn_m1_res1:
	ds_read_b64_tr_b16 v[192:193], v191 offset:0x3200
	ds_read_b64_tr_b16 v[194:195], v191 offset:0x3a00
	s_waitcnt lgkmcnt(4)
	v_mfma_f32_32x32x16_bf16 v[32:47], v[100:103], v[200:203], v[32:47]
	v_exp_f32_e32 v128, v128
	v_exp_f32_e32 v129, v129
	v_exp_f32_e32 v130, v130
	ds_read_b64_tr_b16 v[200:201], v191 offset:0x400
	ds_read_b64_tr_b16 v[202:203], v191 offset:0xc00
	s_waitcnt lgkmcnt(4)
	v_mfma_f32_32x32x16_bf16 v[32:47], v[80:83], v[196:199], v[32:47]
	v_exp_f32_e32 v131, v131
	v_exp_f32_e32 v132, v132
	v_exp_f32_e32 v133, v133
	ds_read_b64_tr_b16 v[196:197], v191 offset:0x1400
	ds_read_b64_tr_b16 v[198:199], v191 offset:0x1c00
	s_waitcnt lgkmcnt(4)
	v_mfma_f32_32x32x16_bf16 v[32:47], v[84:87], v[192:195], v[32:47]
	v_exp_f32_e32 v134, v134
	v_exp_f32_e32 v135, v135
	v_exp_f32_e32 v136, v136
	ds_read_b64_tr_b16 v[192:193], v191 offset:0x2400
	ds_read_b64_tr_b16 v[194:195], v191 offset:0x2c00
	s_waitcnt lgkmcnt(4)
	v_mfma_f32_32x32x16_bf16 v[16:31], v[96:99], v[200:203], v[16:31]
	v_exp_f32_e32 v137, v137
	v_exp_f32_e32 v138, v138
	v_exp_f32_e32 v139, v139
	ds_read_b64_tr_b16 v[200:201], v191 offset:0x3400
	ds_read_b64_tr_b16 v[202:203], v191 offset:0x3c00
	s_waitcnt lgkmcnt(4)
	v_mfma_f32_32x32x16_bf16 v[16:31], v[100:103], v[196:199], v[16:31]
	v_exp_f32_e32 v140, v140
	v_exp_f32_e32 v141, v141
	v_exp_f32_e32 v142, v142
	ds_read_b64_tr_b16 v[196:197], v191 offset:0x600
	ds_read_b64_tr_b16 v[198:199], v191 offset:0xe00
	s_waitcnt lgkmcnt(4)
	v_mfma_f32_32x32x16_bf16 v[16:31], v[80:83], v[192:195], v[16:31]
	v_exp_f32_e32 v143, v143
	v_exp_f32_e32 v112, v112
	v_exp_f32_e32 v113, v113
	ds_read_b64_tr_b16 v[192:193], v191 offset:0x1600
	ds_read_b64_tr_b16 v[194:195], v191 offset:0x1e00
	s_waitcnt lgkmcnt(4)
	v_mfma_f32_32x32x16_bf16 v[16:31], v[84:87], v[200:203], v[16:31]
	v_exp_f32_e32 v114, v114
	v_exp_f32_e32 v115, v115
	v_exp_f32_e32 v116, v116
	ds_read_b64_tr_b16 v[200:201], v191 offset:0x2600
	ds_read_b64_tr_b16 v[202:203], v191 offset:0x2e00
	s_waitcnt lgkmcnt(4)
	v_mfma_f32_32x32x16_bf16 v[0:15], v[96:99], v[196:199], v[0:15]
	v_exp_f32_e32 v117, v117
	v_exp_f32_e32 v118, v118
	v_exp_f32_e32 v119, v119
	ds_read_b64_tr_b16 v[196:197], v191 offset:0x3600
	ds_read_b64_tr_b16 v[198:199], v191 offset:0x3e00
	s_waitcnt lgkmcnt(4)
	v_mfma_f32_32x32x16_bf16 v[0:15], v[100:103], v[192:195], v[0:15]
	v_exp_f32_e32 v120, v120
	v_exp_f32_e32 v121, v121
	v_exp_f32_e32 v122, v122
	s_waitcnt lgkmcnt(2)
	v_mfma_f32_32x32x16_bf16 v[0:15], v[80:83], v[200:203], v[0:15]
	v_exp_f32_e32 v123, v123
	v_exp_f32_e32 v124, v124
	v_exp_f32_e32 v125, v125
	s_waitcnt lgkmcnt(0)
	v_mfma_f32_32x32x16_bf16 v[0:15], v[84:87], v[196:199], v[0:15]
	v_exp_f32_e32 v126, v126
	v_exp_f32_e32 v127, v127
	v_cmp_gt_f32_e32 vcc, 1.0, v190
	s_cbranch_vccz .LBB0_725
	s_and_saveexec_b64 s[52:53], s[0:1]
	ds_write_b32 v180, v190 offset:128
	s_or_b64 exec, exec, s[52:53]
	s_waitcnt lgkmcnt(0)
	v_add_u32_e32 v92, s19, v168
	ds_read_b128 v[80:83], v92 offset:224
	ds_read_b128 v[84:87], v92 offset:192
	ds_read_b128 v[88:91], v92 offset:160
	ds_read_b128 v[92:95], v92 offset:128
	s_waitcnt lgkmcnt(3)
	v_pk_mul_f32 v[60:61], v[60:61], v[80:81]
	s_waitcnt lgkmcnt(2)
	v_pk_mul_f32 v[56:57], v[56:57], v[84:85]
	s_waitcnt lgkmcnt(1)
	v_pk_mul_f32 v[52:53], v[52:53], v[88:89]
	v_pk_mul_f32 v[62:63], v[62:63], v[82:83]
	v_pk_mul_f32 v[58:59], v[58:59], v[86:87]
	v_pk_mul_f32 v[54:55], v[54:55], v[90:91]
	s_waitcnt lgkmcnt(0)
	v_pk_mul_f32 v[50:51], v[50:51], v[94:95]
	v_pk_mul_f32 v[48:49], v[48:49], v[92:93]
	v_pk_mul_f32 v[44:45], v[44:45], v[80:81]
	v_pk_mul_f32 v[40:41], v[40:41], v[84:85]
	v_pk_mul_f32 v[36:37], v[36:37], v[88:89]
	v_pk_mul_f32 v[46:47], v[46:47], v[82:83]
	v_pk_mul_f32 v[42:43], v[42:43], v[86:87]
	v_pk_mul_f32 v[38:39], v[38:39], v[90:91]
	v_pk_mul_f32 v[34:35], v[34:35], v[94:95]
	v_pk_mul_f32 v[32:33], v[32:33], v[92:93]
	v_pk_mul_f32 v[28:29], v[28:29], v[80:81]
	v_pk_mul_f32 v[24:25], v[24:25], v[84:85]
	v_pk_mul_f32 v[20:21], v[20:21], v[88:89]
	v_pk_mul_f32 v[30:31], v[30:31], v[82:83]
	v_pk_mul_f32 v[26:27], v[26:27], v[86:87]
	v_pk_mul_f32 v[22:23], v[22:23], v[90:91]
	v_pk_mul_f32 v[18:19], v[18:19], v[94:95]
	v_pk_mul_f32 v[16:17], v[16:17], v[92:93]
	v_pk_mul_f32 v[12:13], v[12:13], v[80:81]
	v_pk_mul_f32 v[8:9], v[8:9], v[84:85]
	v_pk_mul_f32 v[4:5], v[4:5], v[88:89]
	v_pk_mul_f32 v[14:15], v[14:15], v[82:83]
	v_pk_mul_f32 v[10:11], v[10:11], v[86:87]
	v_pk_mul_f32 v[6:7], v[6:7], v[90:91]
	v_pk_mul_f32 v[2:3], v[2:3], v[94:95]
	v_pk_mul_f32 v[0:1], v[0:1], v[92:93]
.LBB0_725:
	s_add_u32 s48, s4, 0x20000
	s_addc_u32 s49, s5, 0
	s_lshl_b32 s45, s38, 13
	s_add_i32 s45, s45, s39
	s_waitcnt vmcnt(0) lgkmcnt(0)
	s_barrier
	v_add_u32_e32 v187, s43, v186
	ds_read_b128 v[80:83], v187 offset:49152
	ds_read_b128 v[192:195], v187 offset:49664
	s_mov_b32 m0, s45
	v_lshl_add_u64 v[204:205], v[172:173], 0, s[8:9]
	global_load_lds_dwordx4 v[204:205], off
	s_add_i32 s45, s44, s24
	s_mov_b32 m0, s45
	v_lshl_add_u64 v[206:207], s[48:49], 0, v[166:167]
	global_load_lds_dwordx4 v[206:207], off
	s_add_i32 s44, s44, s25
	s_mov_b32 m0, s44
	v_lshl_add_u64 v[204:205], s[48:49], 0, v[170:171]
	global_load_lds_dwordx4 v[204:205], off
	s_waitcnt lgkmcnt(1)
	v_mfma_f32_32x32x16_bf16 v[96:111], v[80:83], v[156:159], v[64:79]
	ds_read_b128 v[196:199], v187 offset:51200
	ds_read_b128 v[200:203], v187 offset:51712
	v_add_f32_e32 v84, 0, v128
	v_add_f32_e32 v85, 0, v129
	v_add_f32_e32 v84, v130, v84
	v_add_f32_e32 v85, v131, v85
	v_cvt_pk_bf16_f32 v128, v128, v129
	v_cvt_pk_bf16_f32 v129, v130, v131
	v_cvt_pk_bf16_f32 v130, v132, v133
	v_cvt_pk_bf16_f32 v131, v134, v135
	s_nop 0
	v_add_f32_e32 v80, v132, v84
	v_add_f32_e32 v81, v133, v85
	v_add_f32_e32 v132, v134, v80
	v_add_f32_e32 v133, v135, v81
	s_waitcnt lgkmcnt(2)
	v_mfma_f32_32x32x16_bf16 v[80:95], v[192:195], v[156:159], v[64:79]
	v_permlane32_swap_b32_e32 v128, v130
	v_permlane32_swap_b32_e32 v129, v131
	s_waitcnt lgkmcnt(1)
	v_mfma_f32_32x32x16_bf16 v[96:111], v[196:199], v[152:155], v[96:111]
	ds_read_b128 v[192:195], v187 offset:53248
	ds_read_b128 v[204:207], v187 offset:53760
	v_add_f32_e32 v132, v136, v132
	v_add_f32_e32 v133, v137, v133
	v_add_f32_e32 v191, v138, v132
	v_add_f32_e32 v208, v139, v133
	v_cvt_pk_bf16_f32 v132, v136, v137
	v_cvt_pk_bf16_f32 v133, v138, v139
	v_cvt_pk_bf16_f32 v134, v140, v141
	v_cvt_pk_bf16_f32 v135, v142, v143
	s_waitcnt lgkmcnt(2)
	v_mfma_f32_32x32x16_bf16 v[80:95], v[200:203], v[152:155], v[80:95]
	v_add_f32_e32 v136, v140, v191
	v_add_f32_e32 v137, v141, v208
	v_add_f32_e32 v191, v142, v136
	v_add_f32_e32 v196, v143, v137
	v_permlane32_swap_b32_e32 v132, v134
	v_permlane32_swap_b32_e32 v133, v135
	s_waitcnt lgkmcnt(1)
	v_mfma_f32_32x32x16_bf16 v[96:111], v[192:195], v[148:151], v[96:111]
	ds_read_b128 v[136:139], v187 offset:55296
	ds_read_b128 v[140:143], v187 offset:55808
	v_add_f32_e32 v187, v112, v191
	v_add_f32_e32 v191, v113, v196
	v_add_f32_e32 v187, v114, v187
	v_add_f32_e32 v191, v115, v191
	v_cvt_pk_bf16_f32 v112, v112, v113
	v_cvt_pk_bf16_f32 v113, v114, v115
	v_cvt_pk_bf16_f32 v114, v116, v117
	v_cvt_pk_bf16_f32 v115, v118, v119
	s_waitcnt lgkmcnt(2)
	v_mfma_f32_32x32x16_bf16 v[80:95], v[204:207], v[148:151], v[80:95]
	v_lshl_add_u32 v208, s42, 14, v185
	ds_read_b64_tr_b16 v[200:201], v208 offset:0
	ds_read_b64_tr_b16 v[202:203], v208 offset:0x800
	v_add_f32_e32 v116, v116, v187
	v_add_f32_e32 v117, v117, v191
	v_add_f32_e32 v116, v118, v116
	v_add_f32_e32 v117, v119, v117
	v_permlane32_swap_b32_e32 v112, v114
	v_permlane32_swap_b32_e32 v113, v115
	s_waitcnt lgkmcnt(3)
	v_mfma_f32_32x32x16_bf16 v[96:111], v[136:139], v[144:147], v[96:111]
	ds_read_b64_tr_b16 v[192:193], v208 offset:0x1000
	ds_read_b64_tr_b16 v[194:195], v208 offset:0x1800
	v_add_f32_e32 v116, v120, v116
	v_add_f32_e32 v117, v121, v117
	v_add_f32_e32 v187, v122, v116
	v_add_f32_e32 v191, v123, v117
	v_cvt_pk_bf16_f32 v116, v120, v121
	v_cvt_pk_bf16_f32 v117, v122, v123
	v_cvt_pk_bf16_f32 v118, v124, v125
	v_cvt_pk_bf16_f32 v119, v126, v127
	s_waitcnt lgkmcnt(4)
	v_mfma_f32_32x32x16_bf16 v[80:95], v[140:143], v[144:147], v[80:95]
	v_add_f32_e32 v120, v124, v187
	v_add_f32_e32 v121, v125, v191
	v_add_f32_e32 v120, v126, v120
	v_add_f32_e32 v121, v127, v121
	v_permlane32_swap_b32_e32 v116, v118
	v_permlane32_swap_b32_e32 v117, v119
	ds_read_b64_tr_b16 v[204:205], v208 offset:0x2000
	ds_read_b64_tr_b16 v[206:207], v208 offset:0x2800
	s_waitcnt lgkmcnt(4)
	v_mfma_f32_32x32x16_bf16 v[48:63], v[128:131], v[200:203], v[48:63]
	v_max_f32_e32 v122, v97, v97
	v_max_f32_e32 v123, v96, v96
	v_max_f32_e32 v122, v123, v122
	v_max3_f32 v123, v99, v100, v101
	v_max3_f32 v122, v122, v98, v102
	v_max3_f32 v123, v123, v104, v105
	ds_read_b64_tr_b16 v[200:201], v208 offset:0x3000
	ds_read_b64_tr_b16 v[202:203], v208 offset:0x3800
	s_waitcnt lgkmcnt(4)
	v_mfma_f32_32x32x16_bf16 v[48:63], v[132:135], v[192:195], v[48:63]
	v_max3_f32 v122, v122, v103, v106
	v_max3_f32 v123, v123, v108, v109
	v_max3_f32 v122, v122, v107, v110
	v_max3_f32 v122, v122, v111, v123
	v_add_f32_e32 v120, v120, v121
	v_mov_b32_e32 v121, v120
	ds_read_b64_tr_b16 v[192:193], v208 offset:0x200
	ds_read_b64_tr_b16 v[194:195], v208 offset:0xa00
	s_waitcnt lgkmcnt(4)
	v_mfma_f32_32x32x16_bf16 v[48:63], v[112:115], v[204:207], v[48:63]
	v_max3_f32 v123, v80, v81, v82
	v_max3_f32 v124, v83, v84, v85
	v_max3_f32 v123, v123, v86, v87
	v_max3_f32 v124, v124, v88, v89
	v_permlane32_swap_b32_e32 v120, v121
	v_max3_f32 v123, v123, v90, v91
	ds_read_b64_tr_b16 v[204:205], v208 offset:0x1200
	ds_read_b64_tr_b16 v[206:207], v208 offset:0x1a00
	s_waitcnt lgkmcnt(4)
	v_mfma_f32_32x32x16_bf16 v[48:63], v[116:119], v[200:203], v[48:63]
	v_max3_f32 v124, v124, v92, v93
	v_max3_f32 v123, v123, v94, v95
	v_max3_f32 v122, v122, v123, v124
	v_mov_b32_e32 v123, v122
	ds_read_b64_tr_b16 v[200:201], v208 offset:0x2200
	ds_read_b64_tr_b16 v[202:203], v208 offset:0x2a00
	s_waitcnt lgkmcnt(4)
	v_mfma_f32_32x32x16_bf16 v[32:47], v[128:131], v[192:195], v[32:47]
	v_permlane32_swap_b32_e32 v122, v123
	v_max_f32_e32 v123, v123, v123
	v_max_f32_e32 v122, v122, v122
	v_max_f32_e32 v122, v122, v123
	v_cmp_lt_f32_e32 vcc, s47, v122
	v_mov_b32_e32 v187, 1.0
	s_cbranch_vccnz .LBB0_733
.Lattn_m1_res2:
	ds_read_b64_tr_b16 v[192:193], v208 offset:0x3200
	ds_read_b64_tr_b16 v[194:195], v208 offset:0x3a00
	s_waitcnt lgkmcnt(4)
	v_mfma_f32_32x32x16_bf16 v[32:47], v[132:135], v[204:207], v[32:47]
	v_exp_f32_e32 v96, v96
	v_exp_f32_e32 v97, v97
	v_exp_f32_e32 v98, v98
	ds_read_b64_tr_b16 v[204:205], v208 offset:0x400
	ds_read_b64_tr_b16 v[206:207], v208 offset:0xc00
	s_waitcnt lgkmcnt(4)
	v_mfma_f32_32x32x16_bf16 v[32:47], v[112:115], v[200:203], v[32:47]
	v_exp_f32_e32 v99, v99
	v_exp_f32_e32 v100, v100
	v_exp_f32_e32 v101, v101
	ds_read_b64_tr_b16 v[200:201], v208 offset:0x1400
	ds_read_b64_tr_b16 v[202:203], v208 offset:0x1c00
	s_waitcnt lgkmcnt(4)
	v_mfma_f32_32x32x16_bf16 v[32:47], v[116:119], v[192:195], v[32:47]
	v_exp_f32_e32 v102, v102
	v_exp_f32_e32 v103, v103
	v_exp_f32_e32 v104, v104
	ds_read_b64_tr_b16 v[192:193], v208 offset:0x2400
	ds_read_b64_tr_b16 v[194:195], v208 offset:0x2c00
	s_waitcnt lgkmcnt(4)
	v_mfma_f32_32x32x16_bf16 v[16:31], v[128:131], v[204:207], v[16:31]
	v_exp_f32_e32 v105, v105
	v_exp_f32_e32 v106, v106
	v_exp_f32_e32 v107, v107
	ds_read_b64_tr_b16 v[204:205], v208 offset:0x3400
	ds_read_b64_tr_b16 v[206:207], v208 offset:0x3c00
	s_waitcnt lgkmcnt(4)
	v_mfma_f32_32x32x16_bf16 v[16:31], v[132:135], v[200:203], v[16:31]
	v_exp_f32_e32 v108, v108
	v_exp_f32_e32 v109, v109
	v_exp_f32_e32 v110, v110
	ds_read_b64_tr_b16 v[200:201], v208 offset:0x600
	ds_read_b64_tr_b16 v[202:203], v208 offset:0xe00
	s_waitcnt lgkmcnt(4)
	v_mfma_f32_32x32x16_bf16 v[16:31], v[112:115], v[192:195], v[16:31]
	v_exp_f32_e32 v111, v111
	v_exp_f32_e32 v80, v80
	v_exp_f32_e32 v81, v81
	ds_read_b64_tr_b16 v[192:193], v208 offset:0x1600
	ds_read_b64_tr_b16 v[194:195], v208 offset:0x1e00
	s_waitcnt lgkmcnt(4)
	v_mfma_f32_32x32x16_bf16 v[16:31], v[116:119], v[204:207], v[16:31]
	v_exp_f32_e32 v82, v82
	v_exp_f32_e32 v83, v83
	v_exp_f32_e32 v84, v84
	ds_read_b64_tr_b16 v[204:205], v208 offset:0x2600
	ds_read_b64_tr_b16 v[206:207], v208 offset:0x2e00
	s_waitcnt lgkmcnt(4)
	v_mfma_f32_32x32x16_bf16 v[0:15], v[128:131], v[200:203], v[0:15]
	v_exp_f32_e32 v85, v85
	v_exp_f32_e32 v86, v86
	v_exp_f32_e32 v87, v87
	ds_read_b64_tr_b16 v[200:201], v208 offset:0x3600
	ds_read_b64_tr_b16 v[202:203], v208 offset:0x3e00
	s_waitcnt lgkmcnt(4)
	v_mfma_f32_32x32x16_bf16 v[0:15], v[132:135], v[192:195], v[0:15]
	v_exp_f32_e32 v88, v88
	v_exp_f32_e32 v89, v89
	v_exp_f32_e32 v90, v90
	s_waitcnt lgkmcnt(2)
	v_mfma_f32_32x32x16_bf16 v[0:15], v[112:115], v[204:207], v[0:15]
	v_exp_f32_e32 v91, v91
	v_exp_f32_e32 v92, v92
	v_exp_f32_e32 v93, v93
	s_waitcnt lgkmcnt(0)
	v_mfma_f32_32x32x16_bf16 v[0:15], v[116:119], v[200:203], v[0:15]
	v_exp_f32_e32 v94, v94
	v_exp_f32_e32 v95, v95
	v_cmp_gt_f32_e32 vcc, 1.0, v187
	s_cbranch_vccz .LBB0_730
	s_and_saveexec_b64 s[52:53], s[0:1]
	ds_write_b32 v180, v187 offset:128
	s_or_b64 exec, exec, s[52:53]
	s_waitcnt lgkmcnt(0)
	v_add_u32_e32 v126, s19, v168
	ds_read_b128 v[112:115], v126 offset:224
	ds_read_b128 v[116:119], v126 offset:192
	ds_read_b128 v[122:125], v126 offset:160
	ds_read_b128 v[126:129], v126 offset:128
	s_waitcnt lgkmcnt(3)
	v_pk_mul_f32 v[60:61], v[60:61], v[112:113]
	s_waitcnt lgkmcnt(2)
	v_pk_mul_f32 v[56:57], v[56:57], v[116:117]
	s_waitcnt lgkmcnt(1)
	v_pk_mul_f32 v[52:53], v[52:53], v[122:123]
	v_pk_mul_f32 v[62:63], v[62:63], v[114:115]
	v_pk_mul_f32 v[58:59], v[58:59], v[118:119]
	v_pk_mul_f32 v[54:55], v[54:55], v[124:125]
	s_waitcnt lgkmcnt(0)
	v_pk_mul_f32 v[50:51], v[50:51], v[128:129]
	v_pk_mul_f32 v[48:49], v[48:49], v[126:127]
	v_pk_mul_f32 v[44:45], v[44:45], v[112:113]
	v_pk_mul_f32 v[40:41], v[40:41], v[116:117]
	v_pk_mul_f32 v[36:37], v[36:37], v[122:123]
	v_pk_mul_f32 v[46:47], v[46:47], v[114:115]
	v_pk_mul_f32 v[42:43], v[42:43], v[118:119]
	v_pk_mul_f32 v[38:39], v[38:39], v[124:125]
	v_pk_mul_f32 v[34:35], v[34:35], v[128:129]
	v_pk_mul_f32 v[32:33], v[32:33], v[126:127]
	v_pk_mul_f32 v[28:29], v[28:29], v[112:113]
	v_pk_mul_f32 v[24:25], v[24:25], v[116:117]
	v_pk_mul_f32 v[20:21], v[20:21], v[122:123]
	v_pk_mul_f32 v[30:31], v[30:31], v[114:115]
	v_pk_mul_f32 v[26:27], v[26:27], v[118:119]
	v_pk_mul_f32 v[22:23], v[22:23], v[124:125]
	v_pk_mul_f32 v[18:19], v[18:19], v[128:129]
	v_pk_mul_f32 v[16:17], v[16:17], v[126:127]
	v_pk_mul_f32 v[12:13], v[12:13], v[112:113]
	v_pk_mul_f32 v[8:9], v[8:9], v[116:117]
	v_pk_mul_f32 v[4:5], v[4:5], v[122:123]
	v_pk_mul_f32 v[14:15], v[14:15], v[114:115]
	v_pk_mul_f32 v[10:11], v[10:11], v[118:119]
	v_pk_mul_f32 v[6:7], v[6:7], v[124:125]
	v_pk_mul_f32 v[2:3], v[2:3], v[128:129]
	v_pk_mul_f32 v[0:1], v[0:1], v[126:127]
